# masked diagonal tile: removed +0.0 row-sum adds and the unused zero fragment, packed adds split to scalar
# speedup vs baseline: 1.0101x; 1.0029x over previous
; template <bool MASKED>
; __device__ __forceinline__ void attn_step(const bf16x8 (&ka)[2][6], const bf16x8 (&va)[2][4], const bf16x8 (&qf)[6], int nvalid, int lane, f32x16& o0, f32x16& o1, float& mrun, float& lsum) {
;     ...
;     {
;         const f32x2 m2 = {mrun, mrun}; f32x2 acc2 = {0.f, 0.f};
; #pragma unroll
;         for (int i = 0; i < 16; i += 2) {
;             f32x2 a = (f32x2){s0[i], s0[i + 1]} - m2, c = (f32x2){s1[i], s1[i + 1]} - m2;
;             a.x = __builtin_amdgcn_exp2f(a.x); a.y = __builtin_amdgcn_exp2f(a.y); c.x = __builtin_amdgcn_exp2f(c.x); c.y = __builtin_amdgcn_exp2f(c.y);
;             acc2 = acc2 + a; acc2 = acc2 + c;
;             s0[i] = a.x; s0[i + 1] = a.y; s1[i] = c.x; s1[i + 1] = c.y;
;         }
;         lsum += acc2.x + acc2.y;
.LBB0_629:
	v_sub_f32_e32 v34, v34, v0
	v_sub_f32_e32 v35, v35, v0
	v_mov_b32_e32 v213, v250
	v_exp_f32_e32 v42, v34
	v_exp_f32_e32 v43, v35
	v_sub_f32_e32 v34, v36, v0
	v_sub_f32_e32 v35, v37, v0
	s_nop 0
	v_exp_f32_e32 v44, v34
	v_exp_f32_e32 v45, v35
	v_sub_f32_e32 v34, v38, v0
	v_sub_f32_e32 v35, v39, v0
	s_nop 0
	v_exp_f32_e32 v38, v34
	v_exp_f32_e32 v39, v35
	v_sub_f32_e32 v34, v40, v0
	v_sub_f32_e32 v35, v41, v0
	v_exp_f32_e32 v40, v34
	v_exp_f32_e32 v41, v35
	v_cvt_pk_bf16_f32 v34, v42, v43
	v_cvt_pk_bf16_f32 v35, v44, v45
	v_cvt_pk_bf16_f32 v36, v38, v39
	v_cvt_pk_bf16_f32 v37, v40, v41
	s_nop 1
	s_waitcnt lgkmcnt(7)
	v_mfma_f32_32x32x16_bf16 v[18:33], v[158:161], v[34:37], v[18:33]
	s_waitcnt lgkmcnt(3)
	v_mfma_f32_32x32x16_bf16 v[2:17], v[162:165], v[34:37], v[2:17]
	v_add_f32_e64 v34, v42, 0
	v_add_f32_e64 v35, v43, 0
	v_add_f32_e64 v34, v44, v34
	v_add_f32_e64 v35, v45, v35
	v_add_f32_e64 v34, v38, v34
	v_add_f32_e64 v35, v39, v35
	v_add_f32_e64 v34, v40, v34
	v_add_f32_e64 v35, v41, v35
	s_waitcnt lgkmcnt(2)
	v_add_f32_e32 v0, v34, v35
	v_add_f32_e32 v249, v249, v0
	s_waitcnt lgkmcnt(1)
	s_waitcnt lgkmcnt(0)
	s_branch .Latt_end
